# v25 plus: fragment ds_reads interleaved between the LDS-DMA issues in the int8 GEMM1 load segments
# baseline (speedup 1.0000x reference)
.LBB0_300:
	s_add_u32 s100, s0, 0xfff80000
	s_addc_u32 s101, s1, -1
	s_add_u32 s28, s0, 0xfff80080
	s_addc_u32 s29, s1, -1
	s_add_i32 s42, 0, 0x10000
	s_cmp_eq_u32 s41, 28
	s_cselect_b32 s31, s18, s29
	s_cselect_b32 s30, s19, s28
	v_add_u32_e32 v0, s42, v199
	s_cselect_b32 s29, s27, s40
	s_cselect_b32 s28, s34, s35
	s_add_i32 s49, 0, 0x14000
	ds_read_b128 v[2:5], v0
	ds_read_b128 v[6:9], v0 offset:1024
	ds_read_b128 v[10:13], v0 offset:2048
	ds_read_b128 v[14:17], v0 offset:3072
	v_add_u32_e32 v0, s49, v199
	ds_read_b128 v[146:149], v0
	ds_read_b128 v[150:153], v0 offset:1024
	ds_read_b128 v[154:157], v0 offset:2048
	ds_read_b128 v[158:161], v0 offset:3072
	s_mov_b32 m0, s15
	ds_read_b128 v[174:177], v250
	ds_read_b128 v[178:181], v250 offset:1024
	global_load_lds_dwordx4 v162, s[100:101]
	ds_read_b128 v[182:185], v250 offset:2048
	ds_read_b128 v[186:189], v250 offset:3072
	s_mov_b32 m0, s88
	s_nop 0
	global_load_lds_dwordx4 v166, s[100:101]
	ds_read_b128 v[190:193], v250 offset:4096
	ds_read_b128 v[200:203], v250 offset:5120
	s_add_i32 m0, s21, 0xc000
	s_nop 0
	global_load_lds_dwordx4 v170, s[0:1]
	ds_read_b128 v[204:207], v250 offset:6144
	ds_read_b128 v[208:211], v250 offset:7168
	s_add_i32 m0, s21, 0xe000
	s_nop 0
	global_load_lds_dwordx4 v172, s[0:1]
	s_waitcnt vmcnt(8)
	s_waitcnt lgkmcnt(0)
	s_barrier
	s_waitcnt lgkmcnt(0)
	v_mfma_i32_16x16x64_i8 v[142:145], v[2:5], v[174:177], v[142:145]
	v_mfma_i32_16x16x64_i8 v[142:145], v[6:9], v[178:181], v[142:145]
	v_mfma_i32_16x16x64_i8 v[134:137], v[2:5], v[182:185], v[134:137]
	v_mfma_i32_16x16x64_i8 v[134:137], v[6:9], v[186:189], v[134:137]
	v_mfma_i32_16x16x64_i8 v[122:125], v[2:5], v[190:193], v[122:125]
	v_mfma_i32_16x16x64_i8 v[122:125], v[6:9], v[200:203], v[122:125]
	v_mfma_i32_16x16x64_i8 v[106:109], v[2:5], v[204:207], v[106:109]
	v_mfma_i32_16x16x64_i8 v[106:109], v[6:9], v[208:211], v[106:109]
	v_mfma_i32_16x16x64_i8 v[138:141], v[10:13], v[174:177], v[138:141]
	v_mfma_i32_16x16x64_i8 v[138:141], v[14:17], v[178:181], v[138:141]
	v_mfma_i32_16x16x64_i8 v[130:133], v[10:13], v[182:185], v[130:133]
	v_mfma_i32_16x16x64_i8 v[130:133], v[14:17], v[186:189], v[130:133]
	v_mfma_i32_16x16x64_i8 v[114:117], v[10:13], v[190:193], v[114:117]
	v_mfma_i32_16x16x64_i8 v[114:117], v[14:17], v[200:203], v[114:117]
	v_mfma_i32_16x16x64_i8 v[98:101], v[10:13], v[204:207], v[98:101]
	v_mfma_i32_16x16x64_i8 v[98:101], v[14:17], v[208:211], v[98:101]
	v_mfma_i32_16x16x64_i8 v[126:129], v[146:149], v[174:177], v[126:129]
	v_mfma_i32_16x16x64_i8 v[126:129], v[150:153], v[178:181], v[126:129]
	v_mfma_i32_16x16x64_i8 v[110:113], v[146:149], v[182:185], v[110:113]
	v_mfma_i32_16x16x64_i8 v[110:113], v[150:153], v[186:189], v[110:113]
	v_mfma_i32_16x16x64_i8 v[94:97], v[146:149], v[190:193], v[94:97]
	v_mfma_i32_16x16x64_i8 v[94:97], v[150:153], v[200:203], v[94:97]
	v_mfma_i32_16x16x64_i8 v[86:89], v[146:149], v[204:207], v[86:89]
	v_mfma_i32_16x16x64_i8 v[86:89], v[150:153], v[208:211], v[86:89]
	v_mfma_i32_16x16x64_i8 v[118:121], v[154:157], v[174:177], v[118:121]
	v_mfma_i32_16x16x64_i8 v[118:121], v[158:161], v[178:181], v[118:121]
	v_mfma_i32_16x16x64_i8 v[102:105], v[154:157], v[182:185], v[102:105]
	v_mfma_i32_16x16x64_i8 v[102:105], v[158:161], v[186:189], v[102:105]
	v_mfma_i32_16x16x64_i8 v[90:93], v[154:157], v[190:193], v[90:93]
	v_mfma_i32_16x16x64_i8 v[90:93], v[158:161], v[200:203], v[90:93]
	v_mfma_i32_16x16x64_i8 v[82:85], v[154:157], v[204:207], v[82:85]
	v_mfma_i32_16x16x64_i8 v[82:85], v[158:161], v[208:211], v[82:85]
	s_barrier
	s_add_i32 s42, s42, s81
	s_mov_b32 m0, s42
	ds_read_b128 v[174:177], v250 offset:16384
	ds_read_b128 v[178:181], v250 offset:17408
	global_load_lds_dwordx4 v164, s[28:29]
	ds_read_b128 v[182:185], v250 offset:18432
	ds_read_b128 v[186:189], v250 offset:19456
	s_add_i32 m0, s42, 0x2000
	s_add_u32 s42, s28, 0x80000
	s_addc_u32 s43, s29, 0
	s_add_i32 s49, s49, s81
	global_load_lds_dwordx4 v168, s[28:29]
	ds_read_b128 v[190:193], v250 offset:20480
	ds_read_b128 v[200:203], v250 offset:21504
	s_mov_b32 m0, s49
	s_nop 0
	global_load_lds_dwordx4 v164, s[42:43]
	ds_read_b128 v[204:207], v250 offset:22528
	ds_read_b128 v[208:211], v250 offset:23552
	s_add_i32 m0, s49, 0x2000
	s_nop 0
	global_load_lds_dwordx4 v168, s[42:43]
	s_waitcnt vmcnt(6)
	s_waitcnt lgkmcnt(0)
	s_barrier
	s_waitcnt lgkmcnt(0)
	v_mfma_i32_16x16x64_i8 v[78:81], v[2:5], v[174:177], v[78:81]
	v_mfma_i32_16x16x64_i8 v[78:81], v[6:9], v[178:181], v[78:81]
	v_mfma_i32_16x16x64_i8 v[74:77], v[10:13], v[174:177], v[74:77]
	v_mfma_i32_16x16x64_i8 v[74:77], v[14:17], v[178:181], v[74:77]
	v_mfma_i32_16x16x64_i8 v[70:73], v[2:5], v[182:185], v[70:73]
	v_mfma_i32_16x16x64_i8 v[70:73], v[6:9], v[186:189], v[70:73]
	v_mfma_i32_16x16x64_i8 v[66:69], v[10:13], v[182:185], v[66:69]
	v_mfma_i32_16x16x64_i8 v[66:69], v[14:17], v[186:189], v[66:69]
	v_mfma_i32_16x16x64_i8 v[54:57], v[2:5], v[190:193], v[54:57]
	v_mfma_i32_16x16x64_i8 v[54:57], v[6:9], v[200:203], v[54:57]
	v_mfma_i32_16x16x64_i8 v[50:53], v[10:13], v[190:193], v[50:53]
	v_mfma_i32_16x16x64_i8 v[50:53], v[14:17], v[200:203], v[50:53]
	v_mfma_i32_16x16x64_i8 v[2:5], v[2:5], v[204:207], v[38:41]
	v_mfma_i32_16x16x64_i8 v[2:5], v[6:9], v[208:211], v[2:5]
	v_mfma_i32_16x16x64_i8 v[6:9], v[10:13], v[204:207], v[34:37]
	v_mfma_i32_16x16x64_i8 v[6:9], v[14:17], v[208:211], v[6:9]
	v_mfma_i32_16x16x64_i8 v[34:37], v[146:149], v[182:185], v[46:49]
	v_mfma_i32_16x16x64_i8 v[46:49], v[150:153], v[186:189], v[34:37]
	v_mfma_i32_16x16x64_i8 v[34:37], v[154:157], v[182:185], v[42:45]
	v_mfma_i32_16x16x64_i8 v[42:45], v[158:161], v[186:189], v[34:37]
	v_mfma_i32_16x16x64_i8 v[30:33], v[146:149], v[190:193], v[30:33]
	v_mfma_i32_16x16x64_i8 v[30:33], v[150:153], v[200:203], v[30:33]
	v_mfma_i32_16x16x64_i8 v[26:29], v[154:157], v[190:193], v[26:29]
	v_mfma_i32_16x16x64_i8 v[26:29], v[158:161], v[200:203], v[26:29]
	v_mfma_i32_16x16x64_i8 v[22:25], v[146:149], v[204:207], v[22:25]
	v_mfma_i32_16x16x64_i8 v[22:25], v[150:153], v[208:211], v[22:25]
	v_mfma_i32_16x16x64_i8 v[18:21], v[154:157], v[204:207], v[18:21]
	v_mfma_i32_16x16x64_i8 v[18:21], v[158:161], v[208:211], v[18:21]
	v_mfma_i32_16x16x64_i8 v[10:13], v[146:149], v[174:177], v[62:65]
	v_mfma_i32_16x16x64_i8 v[10:13], v[150:153], v[178:181], v[10:13]
	v_mfma_i32_16x16x64_i8 v[14:17], v[154:157], v[174:177], v[58:61]
	v_mfma_i32_16x16x64_i8 v[14:17], v[158:161], v[178:181], v[14:17]
	s_barrier
	s_add_i32 s42, 0, 0x18000
	v_add_u32_e32 v0, s42, v199
	s_add_i32 s43, 0, 0x1c000
	ds_read_b128 v[34:37], v0
	ds_read_b128 v[38:41], v0 offset:1024
	ds_read_b128 v[58:61], v0 offset:2048
	ds_read_b128 v[62:65], v0 offset:3072
	v_add_u32_e32 v0, s43, v199
	ds_read_b128 v[146:149], v0
	ds_read_b128 v[150:153], v0 offset:1024
	ds_read_b128 v[154:157], v0 offset:2048
	ds_read_b128 v[158:161], v0 offset:3072
	s_mov_b32 m0, s21
	ds_read_b128 v[174:177], v250 offset:32768
	ds_read_b128 v[178:181], v250 offset:33792
	global_load_lds_dwordx4 v162, s[30:31]
	ds_read_b128 v[182:185], v250 offset:34816
	ds_read_b128 v[186:189], v250 offset:35840
	s_mov_b32 m0, s57
	s_nop 0
	global_load_lds_dwordx4 v166, s[30:31]
	ds_read_b128 v[190:193], v250 offset:36864
	ds_read_b128 v[200:203], v250 offset:37888
	s_add_u32 s30, s30, 0x80000
	s_addc_u32 s31, s31, 0
	s_mov_b32 m0, s73
	s_nop 0
	global_load_lds_dwordx4 v162, s[30:31]
	ds_read_b128 v[204:207], v250 offset:38912
	ds_read_b128 v[208:211], v250 offset:39936
	s_mov_b32 m0, s76
	s_nop 0
	global_load_lds_dwordx4 v166, s[30:31]
	s_waitcnt vmcnt(8)
	s_waitcnt lgkmcnt(0)
	s_barrier
	s_waitcnt lgkmcnt(0)
	v_mfma_i32_16x16x64_i8 v[142:145], v[34:37], v[174:177], v[142:145]
	v_mfma_i32_16x16x64_i8 v[142:145], v[38:41], v[178:181], v[142:145]
	v_mfma_i32_16x16x64_i8 v[134:137], v[34:37], v[182:185], v[134:137]
	v_mfma_i32_16x16x64_i8 v[134:137], v[38:41], v[186:189], v[134:137]
	v_mfma_i32_16x16x64_i8 v[122:125], v[34:37], v[190:193], v[122:125]
	v_mfma_i32_16x16x64_i8 v[122:125], v[38:41], v[200:203], v[122:125]
	v_mfma_i32_16x16x64_i8 v[106:109], v[34:37], v[204:207], v[106:109]
	v_mfma_i32_16x16x64_i8 v[106:109], v[38:41], v[208:211], v[106:109]
	v_mfma_i32_16x16x64_i8 v[138:141], v[58:61], v[174:177], v[138:141]
	v_mfma_i32_16x16x64_i8 v[138:141], v[62:65], v[178:181], v[138:141]
	v_mfma_i32_16x16x64_i8 v[130:133], v[58:61], v[182:185], v[130:133]
	v_mfma_i32_16x16x64_i8 v[130:133], v[62:65], v[186:189], v[130:133]
	v_mfma_i32_16x16x64_i8 v[114:117], v[58:61], v[190:193], v[114:117]
	v_mfma_i32_16x16x64_i8 v[114:117], v[62:65], v[200:203], v[114:117]
	v_mfma_i32_16x16x64_i8 v[98:101], v[58:61], v[204:207], v[98:101]
	v_mfma_i32_16x16x64_i8 v[98:101], v[62:65], v[208:211], v[98:101]
	v_mfma_i32_16x16x64_i8 v[126:129], v[146:149], v[174:177], v[126:129]
	v_mfma_i32_16x16x64_i8 v[126:129], v[150:153], v[178:181], v[126:129]
	v_mfma_i32_16x16x64_i8 v[110:113], v[146:149], v[182:185], v[110:113]
	v_mfma_i32_16x16x64_i8 v[110:113], v[150:153], v[186:189], v[110:113]
	v_mfma_i32_16x16x64_i8 v[94:97], v[146:149], v[190:193], v[94:97]
	v_mfma_i32_16x16x64_i8 v[94:97], v[150:153], v[200:203], v[94:97]
	v_mfma_i32_16x16x64_i8 v[86:89], v[146:149], v[204:207], v[86:89]
	v_mfma_i32_16x16x64_i8 v[86:89], v[150:153], v[208:211], v[86:89]
	v_mfma_i32_16x16x64_i8 v[118:121], v[154:157], v[174:177], v[118:121]
	v_mfma_i32_16x16x64_i8 v[118:121], v[158:161], v[178:181], v[118:121]
	v_mfma_i32_16x16x64_i8 v[102:105], v[154:157], v[182:185], v[102:105]
	v_mfma_i32_16x16x64_i8 v[102:105], v[158:161], v[186:189], v[102:105]
	v_mfma_i32_16x16x64_i8 v[90:93], v[154:157], v[190:193], v[90:93]
	v_mfma_i32_16x16x64_i8 v[90:93], v[158:161], v[200:203], v[90:93]
	v_mfma_i32_16x16x64_i8 v[82:85], v[154:157], v[204:207], v[82:85]
	v_mfma_i32_16x16x64_i8 v[82:85], v[158:161], v[208:211], v[82:85]
	s_barrier
	s_add_i32 s30, s42, s81
	s_add_u32 s98, s28, 0x80
	s_addc_u32 s99, s29, 0
	s_mov_b32 m0, s30
	ds_read_b128 v[174:177], v250 offset:49152
	ds_read_b128 v[178:181], v250 offset:50176
	global_load_lds_dwordx4 v164, s[98:99]
	ds_read_b128 v[182:185], v250 offset:51200
	ds_read_b128 v[186:189], v250 offset:52224
	s_add_i32 m0, s30, 0x2000
	s_add_u32 s28, s28, 0x80080
	s_addc_u32 s29, s29, 0
	s_add_i32 s30, s43, s81
	global_load_lds_dwordx4 v168, s[98:99]
	ds_read_b128 v[190:193], v250 offset:53248
	ds_read_b128 v[200:203], v250 offset:54272
	s_mov_b32 m0, s30
	s_nop 0
	global_load_lds_dwordx4 v164, s[28:29]
	ds_read_b128 v[204:207], v250 offset:55296
	ds_read_b128 v[208:211], v250 offset:56320
	s_add_i32 m0, s30, 0x2000
	s_nop 0
	global_load_lds_dwordx4 v168, s[28:29]
	s_waitcnt vmcnt(6)
	s_waitcnt lgkmcnt(0)
	s_barrier
	s_waitcnt lgkmcnt(0)
	v_mfma_i32_16x16x64_i8 v[78:81], v[34:37], v[174:177], v[78:81]
	v_mfma_i32_16x16x64_i8 v[78:81], v[38:41], v[178:181], v[78:81]
	v_mfma_i32_16x16x64_i8 v[70:73], v[34:37], v[182:185], v[70:73]
	v_mfma_i32_16x16x64_i8 v[70:73], v[38:41], v[186:189], v[70:73]
	v_mfma_i32_16x16x64_i8 v[54:57], v[34:37], v[190:193], v[54:57]
	v_mfma_i32_16x16x64_i8 v[54:57], v[38:41], v[200:203], v[54:57]
	v_mfma_i32_16x16x64_i8 v[2:5], v[34:37], v[204:207], v[2:5]
	v_mfma_i32_16x16x64_i8 v[38:41], v[38:41], v[208:211], v[2:5]
	v_mfma_i32_16x16x64_i8 v[74:77], v[58:61], v[174:177], v[74:77]
	v_mfma_i32_16x16x64_i8 v[74:77], v[62:65], v[178:181], v[74:77]
	v_mfma_i32_16x16x64_i8 v[66:69], v[58:61], v[182:185], v[66:69]
	v_mfma_i32_16x16x64_i8 v[66:69], v[62:65], v[186:189], v[66:69]
	v_mfma_i32_16x16x64_i8 v[50:53], v[58:61], v[190:193], v[50:53]
	v_mfma_i32_16x16x64_i8 v[50:53], v[62:65], v[200:203], v[50:53]
	v_mfma_i32_16x16x64_i8 v[2:5], v[58:61], v[204:207], v[6:9]
	v_mfma_i32_16x16x64_i8 v[34:37], v[62:65], v[208:211], v[2:5]
	v_mfma_i32_16x16x64_i8 v[2:5], v[146:149], v[174:177], v[10:13]
	v_mfma_i32_16x16x64_i8 v[62:65], v[150:153], v[178:181], v[2:5]
	v_mfma_i32_16x16x64_i8 v[2:5], v[154:157], v[174:177], v[14:17]
	v_mfma_i32_16x16x64_i8 v[58:61], v[158:161], v[178:181], v[2:5]
	v_mfma_i32_16x16x64_i8 v[2:5], v[146:149], v[182:185], v[46:49]
	v_mfma_i32_16x16x64_i8 v[46:49], v[150:153], v[186:189], v[2:5]
	v_mfma_i32_16x16x64_i8 v[2:5], v[154:157], v[182:185], v[42:45]
	v_mfma_i32_16x16x64_i8 v[42:45], v[158:161], v[186:189], v[2:5]
	v_mfma_i32_16x16x64_i8 v[2:5], v[146:149], v[190:193], v[30:33]
	v_mfma_i32_16x16x64_i8 v[30:33], v[150:153], v[200:203], v[2:5]
	v_mfma_i32_16x16x64_i8 v[2:5], v[154:157], v[190:193], v[26:29]
	v_mfma_i32_16x16x64_i8 v[26:29], v[158:161], v[200:203], v[2:5]
	v_mfma_i32_16x16x64_i8 v[2:5], v[146:149], v[204:207], v[22:25]
	v_mfma_i32_16x16x64_i8 v[22:25], v[150:153], v[208:211], v[2:5]
	v_mfma_i32_16x16x64_i8 v[2:5], v[154:157], v[204:207], v[18:21]
	v_mfma_i32_16x16x64_i8 v[18:21], v[158:161], v[208:211], v[2:5]
	s_barrier
	s_add_i32 s41, s41, 2
	s_add_u32 s0, s0, 0x100
	s_addc_u32 s1, s1, 0
	s_add_u32 s35, s35, 0x100
	s_addc_u32 s40, s40, 0
	s_cmp_gt_u32 s41, 29
	s_cbranch_scc0 .LBB0_300
	s_and_b64 vcc, exec, s[52:53]
	s_cbranch_vccz .LBB0_303
	s_barrier
